# xblk conversion moved inside the FFN1-in unit loop at a per-WG staggered unit index with a hand-pipelined loop (on top of peel+NSA+WINROWS)
# speedup vs baseline: 1.0072x; 1.0072x over previous
; #define PH_BEGIN() do { int t_ = threadIdx.x; asm volatile("" : "+v"(t_)); F.tid = t_; F.lane = t_ & 63; F.wave = __builtin_amdgcn_readfirstlane(t_ >> 6); } while (0)
; DI void xblk_part(Frame& F, int rank, int nranks) {
;     const int gw = rank * NWAVES + F.wave, NGW = nranks * NWAVES, lane = F.lane;
;     for (int it0 = gw * 4; it0 < NDB * 2048; it0 += NGW * 4) {
; __global__ void __launch_bounds__(NWAVES * 64, 2) hybrid_fwd(Args args) {
;     ...
;     if (IN(1)) { PH_BEGIN(); pg8::Gemm g{F.XB, F.W1A, MTOT, 2 * DFF, DM}; pg8::StaticOrder S; S.init(MTOT, 2 * DFF, F.G, bx); EpiSwiGLU E{F.HB};
;         if (F.vcu & 1) { xblk_part(F, F.vcu, F.G); __syncthreads(); }
.LBB0_85:
	v_readlane_b32 s2, v253, 15
	v_readlane_b32 s3, v253, 16
	s_cmp_lt_i32 s2, 2
	v_readlane_b32 s8, v253, 17
	s_cselect_b64 s[2:3], -1, 0
	v_readlane_b32 s9, v253, 18
	s_add_u32 s4, s8, 0x2e00000
	s_addc_u32 s5, s9, 0
	s_add_u32 s10, s8, 0x5b00000
	s_addc_u32 s11, s9, 0
	v_writelane_b32 v253, s10, 43
	s_nop 1
	v_writelane_b32 v253, s11, 44
	s_add_u32 s10, s8, 0xea00000
	s_addc_u32 s11, s9, 0
	v_writelane_b32 v253, s10, 45
	s_add_u32 s62, s8, 0x3c400000
	s_addc_u32 s63, s9, 0
	v_writelane_b32 v253, s11, 46
	s_and_b64 s[2:3], s[2:3], s[0:1]
	s_mov_b32 s0, s66
	v_writelane_b32 v253, s0, 47
	s_andn2_b64 vcc, exec, s[2:3]
	s_nop 0
	v_writelane_b32 v253, s1, 48
	v_writelane_b32 v253, s64, 49
	v_writelane_b32 v253, s65, 51
	v_writelane_b32 v253, s62, 53
	s_nop 1
	v_writelane_b32 v253, s63, 54
	s_cbranch_vccnz .LBB0_139
	v_mov_b32_e32 v146, v0
	s_nop 0
	v_readfirstlane_b32 s0, v146
	s_ashr_i32 s28, s0, 6
	s_bitcmp0_b32 s96, 0
	s_cselect_b64 s[8:9], -1, 0
	v_and_b32_e32 v1, 63, v146
	s_and_b64 vcc, exec, s[8:9]
	s_cbranch_vccnz .LBB0_91
	s_lshl_b32 s0, s96, 5
	s_lshl_b32 s1, s28, 2
	s_add_i32 s12, s1, s0
	s_cmp_gt_i32 s12, 0x3ffff
	s_branch .LBB0_90
	s_lshl_b32 s0, s96, 12
	s_lshl_b32 s1, s28, 9
	v_lshlrev_b32_e32 v2, 2, v1
	s_add_i32 s14, s0, s1
	s_lshl_b32 s0, s96, 11
	s_lshl_b32 s1, s28, 8
	v_or_b32_e32 v6, 0x100, v2
	v_and_b32_e32 v8, 60, v2
	s_add_i32 s16, s0, s1
	s_lshl_b32 s0, s96, 14
	s_lshl_b32 s1, s28, 11
	v_mov_b32_e32 v3, 0
	v_lshrrev_b32_e32 v4, 4, v1
	s_lshl_b32 s13, s78, 5
	s_lshl_b32 s15, s78, 12
	s_lshl_b32 s17, s78, 11
	s_add_i32 s18, s0, s1
	s_lshl_b32 s19, s78, 14
	s_mov_b32 s1, 0
	v_lshlrev_b32_e32 v5, 2, v2
	v_lshlrev_b32_e32 v6, 2, v6
	v_lshlrev_b32_e32 v2, 1, v8
	s_mov_b64 s[10:11], 0x8800000

; DI unsigned pk2(float lo, float hi) { f32x2 v = {lo, hi}; bf16x2_t b = __builtin_convertvector(v, bf16x2_t); return __builtin_bit_cast(unsigned, b); }
; DI void xblk_part(Frame& F, int rank, int nranks) {
;     const int gw = rank * NWAVES + F.wave, NGW = nranks * NWAVES, lane = F.lane;
;     for (int it0 = gw * 4; it0 < NDB * 2048; it0 += NGW * 4) {
;         f32x4 v[4][2];
; #pragma unroll
;         for (int q = 0; q < 4; ++q) { const int it = it0 + q, s = it >> 11, row = it & 2047; const int page = F.ptab[s * 16 + (row >> 7)];
;             const float* src = F.c_cmp + ((size_t)page * 128 + (row & 127)) * 512;
;             v[q][0] = __builtin_nontemporal_load((const f32x4*)(src + 4 * lane)); v[q][1] = __builtin_nontemporal_load((const f32x4*)(src + 4 * (lane + 64))); }
; #pragma unroll
;         for (int q = 0; q < 4; ++q) { const int it = it0 + q, s = it >> 11, row = it & 2047;
; #pragma unroll
;             for (int j = 0; j < 2; ++j) { const int e = lane + 64 * j, kvsel = e >> 6, h = (e >> 4) & 3, d4 = (e & 15) * 4;
;                 u32x2 w; w.x = pk2(v[q][j][0], v[q][j][1]); w.y = pk2(v[q][j][2], v[q][j][3]);
;                 *(u32x2*)(F.XBLK + ((size_t)kvsel * XROWS + (size_t)(s * 4 + h) * 128 + (row >> 4)) * 1024 + (row & 15) * 64 + d4) = w; } }
.LBB0_97:
	s_and_b32 s84, s96, 7
	s_mul_i32 s84, s84, 11
	s_lshr_b32 s84, s84, 3
	s_cmp_lg_u32 s57, s84
	s_cbranch_scc1 .Lxblk_skip
	s_lshl_b32 s80, s96, 5
	s_lshl_b32 s84, s28, 2
	s_add_i32 s80, s80, s84
	s_cmp_lt_i32 s80, 0x40000
	s_cbranch_scc0 .Lxblk_skip
	s_lshl_b32 s81, s78, 5
	v_readlane_b32 s70, v253, 53
	v_readlane_b32 s71, v253, 54
	v_mbcnt_lo_u32_b32 v55, -1, 0
	v_mbcnt_hi_u32_b32 v55, -1, v55
	v_lshlrev_b32_e32 v50, 4, v55
	v_bfe_u32 v51, v55, 4, 2
	v_lshlrev_b32_e32 v51, 18, v51
	v_and_b32_e32 v52, 15, v55
	v_lshl_add_u32 v51, v52, 3, v51
	v_add_u32_e32 v52, 0x8800000, v51
	s_mov_b32 s82, s80
	s_lshr_b32 s84, s82, 11
	s_lshl_b32 s84, s84, 4
	s_bfe_u32 s85, s82, 0x40007
	s_or_b32 s84, s84, s85
	s_lshl_b32 s84, s84, 2
	s_add_u32 s72, s48, s84
	s_addc_u32 s73, s49, 0
	s_load_dword s84, s[72:73], 0x0
	s_and_b32 s85, s82, 0x7f
	s_lshl_b32 s85, s85, 11
	s_waitcnt lgkmcnt(0)
	s_mov_b32 s87, 0
	s_mov_b32 s86, s84
	s_lshl_b64 s[86:87], s[86:87], 18
	s_add_u32 s68, s40, s86
	s_addc_u32 s69, s41, s87
	s_add_u32 s68, s68, s85
	s_addc_u32 s69, s69, 0
	global_load_dwordx4 v[64:67], v50, s[68:69] nt
	global_load_dwordx4 v[68:71], v50, s[68:69] offset:1024 nt
	global_load_dwordx4 v[72:75], v50, s[68:69] offset:2048 nt
	global_load_dwordx4 v[76:79], v50, s[68:69] offset:3072 nt
	s_add_u32 s68, s68, 0x1000
	s_addc_u32 s69, s69, 0
	global_load_dwordx4 v[80:83], v50, s[68:69] nt
	global_load_dwordx4 v[84:87], v50, s[68:69] offset:1024 nt
	global_load_dwordx4 v[88:91], v50, s[68:69] offset:2048 nt
	global_load_dwordx4 v[92:95], v50, s[68:69] offset:3072 nt
	s_add_i32 s83, s80, s81
	s_cmp_lt_i32 s83, 0x40000
	s_cselect_b32 s83, s83, s80
	s_lshr_b32 s84, s83, 11
	s_lshl_b32 s84, s84, 4
	s_bfe_u32 s85, s83, 0x40007
	s_or_b32 s84, s84, s85
	s_lshl_b32 s84, s84, 2
	s_add_u32 s72, s48, s84
	s_addc_u32 s73, s49, 0
	s_load_dword s84, s[72:73], 0x0
	s_and_b32 s85, s83, 0x7f
	s_lshl_b32 s85, s85, 11
	s_waitcnt lgkmcnt(0)
	s_mov_b32 s87, 0
	s_mov_b32 s86, s84
	s_lshl_b64 s[86:87], s[86:87], 18
	s_add_u32 s68, s40, s86
	s_addc_u32 s69, s41, s87
	s_add_u32 s68, s68, s85
	s_addc_u32 s69, s69, 0
	global_load_dwordx4 v[96:99], v50, s[68:69] nt
	global_load_dwordx4 v[100:103], v50, s[68:69] offset:1024 nt
	global_load_dwordx4 v[104:107], v50, s[68:69] offset:2048 nt
	global_load_dwordx4 v[108:111], v50, s[68:69] offset:3072 nt
	s_add_u32 s68, s68, 0x1000
	s_addc_u32 s69, s69, 0
	global_load_dwordx4 v[112:115], v50, s[68:69] nt
	global_load_dwordx4 v[116:119], v50, s[68:69] offset:1024 nt
	global_load_dwordx4 v[120:123], v50, s[68:69] offset:2048 nt
	global_load_dwordx4 v[124:127], v50, s[68:69] offset:3072 nt
	s_waitcnt vmcnt(8)
	s_lshr_b32 s84, s82, 11
	s_lshl_b32 s84, s84, 20
	s_bfe_u32 s85, s82, 0x70004
	s_lshl_b32 s85, s85, 11
	s_add_u32 s84, s84, s85
	s_and_b32 s85, s82, 15
	s_lshl_b32 s85, s85, 7
	s_add_u32 s84, s84, s85
	v_add_u32_e32 v53, s84, v51
	v_add_u32_e32 v54, s84, v52
	v_cvt_pk_bf16_f32 v56, v64, v65
	v_cvt_pk_bf16_f32 v57, v66, v67
	global_store_dwordx2 v53, v[56:57], s[70:71]
	v_cvt_pk_bf16_f32 v58, v68, v69
	v_cvt_pk_bf16_f32 v59, v70, v71
	global_store_dwordx2 v54, v[58:59], s[70:71]
	v_cvt_pk_bf16_f32 v60, v72, v73
	v_cvt_pk_bf16_f32 v61, v74, v75
	global_store_dwordx2 v53, v[60:61], s[70:71] offset:128
	v_cvt_pk_bf16_f32 v62, v76, v77
	v_cvt_pk_bf16_f32 v63, v78, v79
	global_store_dwordx2 v54, v[62:63], s[70:71] offset:128
	v_cvt_pk_bf16_f32 v56, v80, v81
	v_cvt_pk_bf16_f32 v57, v82, v83
	global_store_dwordx2 v53, v[56:57], s[70:71] offset:256
	v_cvt_pk_bf16_f32 v58, v84, v85
	v_cvt_pk_bf16_f32 v59, v86, v87
	global_store_dwordx2 v54, v[58:59], s[70:71] offset:256
	v_cvt_pk_bf16_f32 v60, v88, v89
	v_cvt_pk_bf16_f32 v61, v90, v91
	global_store_dwordx2 v53, v[60:61], s[70:71] offset:384
	v_cvt_pk_bf16_f32 v62, v92, v93
	v_cvt_pk_bf16_f32 v63, v94, v95
	global_store_dwordx2 v54, v[62:63], s[70:71] offset:384
	s_lshl_b32 s88, s81, 1
	s_add_i32 s82, s80, s88
	s_cmp_lt_i32 s82, 0x40000
	s_cselect_b32 s82, s82, s80
	s_lshr_b32 s84, s82, 11
	s_lshl_b32 s84, s84, 4
	s_bfe_u32 s85, s82, 0x40007
	s_or_b32 s84, s84, s85
	s_lshl_b32 s84, s84, 2
	s_add_u32 s72, s48, s84
	s_addc_u32 s73, s49, 0
	s_load_dword s84, s[72:73], 0x0
	s_and_b32 s85, s82, 0x7f
	s_lshl_b32 s85, s85, 11
	s_waitcnt lgkmcnt(0)
	s_mov_b32 s87, 0
	s_mov_b32 s86, s84
	s_lshl_b64 s[86:87], s[86:87], 18
	s_add_u32 s68, s40, s86
	s_addc_u32 s69, s41, s87
	s_add_u32 s68, s68, s85
	s_addc_u32 s69, s69, 0
	global_load_dwordx4 v[64:67], v50, s[68:69] nt
	global_load_dwordx4 v[68:71], v50, s[68:69] offset:1024 nt
	global_load_dwordx4 v[72:75], v50, s[68:69] offset:2048 nt
	global_load_dwordx4 v[76:79], v50, s[68:69] offset:3072 nt
	s_add_u32 s68, s68, 0x1000
	s_addc_u32 s69, s69, 0
	global_load_dwordx4 v[80:83], v50, s[68:69] nt
	global_load_dwordx4 v[84:87], v50, s[68:69] offset:1024 nt
	global_load_dwordx4 v[88:91], v50, s[68:69] offset:2048 nt
	global_load_dwordx4 v[92:95], v50, s[68:69] offset:3072 nt
; DI unsigned pk2(float lo, float hi) { f32x2 v = {lo, hi}; bf16x2_t b = __builtin_convertvector(v, bf16x2_t); return __builtin_bit_cast(unsigned, b); }
;     DI bool next(int i, pg8::Unit& u) const { const int L = i * G + c; if (L >= 2 * (XROWS / 256)) return false; u.pm = L; u.pn = L / (XROWS / 256); u.kb = 0; return true; }
;     DI bool next(int i, pg8::Unit& u) const { const int L = i * G + c; if (L >= 32 * NSPLIT) return false; const int t = L / NSPLIT, ks = L % NSPLIT; u.pm = MP / 256 + (t >> 3); u.pn = t & 7; u.kb = ks * kslice_bytes; return true; }
;     __host__ __device__ bool next(int i, Unit& u) const {
;         const long L = (long)i * G + c; if (L >= nwg) return false;
;         int wgid = (int)L; { const int q = nwg / NXCD, r = nwg % NXCD, xcd = wgid % NXCD, off = wgid / NXCD; wgid = (xcd < r ? xcd * (q + 1) : r * (q + 1) + (xcd - r) * q) + off; }
;         const int nig = WGM * nN, gid = wgid / nig, fm = gid * WGM, gsz = (nM - fm) < WGM ? (nM - fm) : WGM;
;         u.pm = fm + ((wgid % nig) % gsz); u.pn = (wgid % nig) / gsz; u.kb = 0; return true;
; DI void xblk_part(Frame& F, int rank, int nranks) {
;     const int gw = rank * NWAVES + F.wave, NGW = nranks * NWAVES, lane = F.lane;
;     for (int it0 = gw * 4; it0 < NDB * 2048; it0 += NGW * 4) {
;         f32x4 v[4][2];
; #pragma unroll
;         for (int q = 0; q < 4; ++q) { const int it = it0 + q, s = it >> 11, row = it & 2047; const int page = F.ptab[s * 16 + (row >> 7)];
;             const float* src = F.c_cmp + ((size_t)page * 128 + (row & 127)) * 512;
;             v[q][0] = __builtin_nontemporal_load((const f32x4*)(src + 4 * lane)); v[q][1] = __builtin_nontemporal_load((const f32x4*)(src + 4 * (lane + 64))); }
; #pragma unroll
;         for (int q = 0; q < 4; ++q) { const int it = it0 + q, s = it >> 11, row = it & 2047;
; #pragma unroll
;             for (int j = 0; j < 2; ++j) { const int e = lane + 64 * j, kvsel = e >> 6, h = (e >> 4) & 3, d4 = (e & 15) * 4;
;                 u32x2 w; w.x = pk2(v[q][j][0], v[q][j][1]); w.y = pk2(v[q][j][2], v[q][j][3]);
;                 *(u32x2*)(F.XBLK + ((size_t)kvsel * XROWS + (size_t)(s * 4 + h) * 128 + (row >> 4)) * 1024 + (row & 15) * 64 + d4) = w; } }
;     }
.Lxblk_loop:
	s_add_i32 s89, s80, s81
	s_cmp_lt_i32 s89, 0x40000
	s_cbranch_scc0 .Lxblk_exit
	s_waitcnt vmcnt(16)
	s_lshr_b32 s84, s83, 11
	s_lshl_b32 s84, s84, 20
	s_bfe_u32 s85, s83, 0x70004
	s_lshl_b32 s85, s85, 11
	s_add_u32 s84, s84, s85
	s_and_b32 s85, s83, 15
	s_lshl_b32 s85, s85, 7
	s_add_u32 s84, s84, s85
	v_add_u32_e32 v53, s84, v51
	v_add_u32_e32 v54, s84, v52
	v_cvt_pk_bf16_f32 v56, v96, v97
	v_cvt_pk_bf16_f32 v57, v98, v99
	global_store_dwordx2 v53, v[56:57], s[70:71]
	v_cvt_pk_bf16_f32 v58, v100, v101
	v_cvt_pk_bf16_f32 v59, v102, v103
	global_store_dwordx2 v54, v[58:59], s[70:71]
	v_cvt_pk_bf16_f32 v60, v104, v105
	v_cvt_pk_bf16_f32 v61, v106, v107
	global_store_dwordx2 v53, v[60:61], s[70:71] offset:128
	v_cvt_pk_bf16_f32 v62, v108, v109
	v_cvt_pk_bf16_f32 v63, v110, v111
	global_store_dwordx2 v54, v[62:63], s[70:71] offset:128
	v_cvt_pk_bf16_f32 v56, v112, v113
	v_cvt_pk_bf16_f32 v57, v114, v115
	global_store_dwordx2 v53, v[56:57], s[70:71] offset:256
	v_cvt_pk_bf16_f32 v58, v116, v117
	v_cvt_pk_bf16_f32 v59, v118, v119
	global_store_dwordx2 v54, v[58:59], s[70:71] offset:256
	v_cvt_pk_bf16_f32 v60, v120, v121
	v_cvt_pk_bf16_f32 v61, v122, v123
	global_store_dwordx2 v53, v[60:61], s[70:71] offset:384
	v_cvt_pk_bf16_f32 v62, v124, v125
	v_cvt_pk_bf16_f32 v63, v126, v127
	global_store_dwordx2 v54, v[62:63], s[70:71] offset:384
	s_add_i32 s83, s89, s88
	s_cmp_lt_i32 s83, 0x40000
	s_cselect_b32 s83, s83, s80
	s_lshr_b32 s84, s83, 11
	s_lshl_b32 s84, s84, 4
	s_bfe_u32 s85, s83, 0x40007
	s_or_b32 s84, s84, s85
	s_lshl_b32 s84, s84, 2
	s_add_u32 s72, s48, s84
	s_addc_u32 s73, s49, 0
	s_load_dword s84, s[72:73], 0x0
	s_and_b32 s85, s83, 0x7f
	s_lshl_b32 s85, s85, 11
	s_waitcnt lgkmcnt(0)
	s_mov_b32 s87, 0
	s_mov_b32 s86, s84
	s_lshl_b64 s[86:87], s[86:87], 18
	s_add_u32 s68, s40, s86
	s_addc_u32 s69, s41, s87
	s_add_u32 s68, s68, s85
	s_addc_u32 s69, s69, 0
	global_load_dwordx4 v[96:99], v50, s[68:69] nt
	global_load_dwordx4 v[100:103], v50, s[68:69] offset:1024 nt
	global_load_dwordx4 v[104:107], v50, s[68:69] offset:2048 nt
	global_load_dwordx4 v[108:111], v50, s[68:69] offset:3072 nt
	s_add_u32 s68, s68, 0x1000
	s_addc_u32 s69, s69, 0
	global_load_dwordx4 v[112:115], v50, s[68:69] nt
	global_load_dwordx4 v[116:119], v50, s[68:69] offset:1024 nt
	global_load_dwordx4 v[120:123], v50, s[68:69] offset:2048 nt
	global_load_dwordx4 v[124:127], v50, s[68:69] offset:3072 nt
	s_add_i32 s89, s80, s88
	s_cmp_lt_i32 s89, 0x40000
	s_cbranch_scc0 .Lxblk_exit
	s_waitcnt vmcnt(16)
	s_lshr_b32 s84, s82, 11
	s_lshl_b32 s84, s84, 20
	s_bfe_u32 s85, s82, 0x70004
	s_lshl_b32 s85, s85, 11
	s_add_u32 s84, s84, s85
	s_and_b32 s85, s82, 15
	s_lshl_b32 s85, s85, 7
	s_add_u32 s84, s84, s85
	v_add_u32_e32 v53, s84, v51
	v_add_u32_e32 v54, s84, v52
	v_cvt_pk_bf16_f32 v56, v64, v65
	v_cvt_pk_bf16_f32 v57, v66, v67
	global_store_dwordx2 v53, v[56:57], s[70:71]
	v_cvt_pk_bf16_f32 v58, v68, v69
	v_cvt_pk_bf16_f32 v59, v70, v71
	global_store_dwordx2 v54, v[58:59], s[70:71]
	v_cvt_pk_bf16_f32 v60, v72, v73
	v_cvt_pk_bf16_f32 v61, v74, v75
	global_store_dwordx2 v53, v[60:61], s[70:71] offset:128
	v_cvt_pk_bf16_f32 v62, v76, v77
	v_cvt_pk_bf16_f32 v63, v78, v79
	global_store_dwordx2 v54, v[62:63], s[70:71] offset:128
	v_cvt_pk_bf16_f32 v56, v80, v81
	v_cvt_pk_bf16_f32 v57, v82, v83
	global_store_dwordx2 v53, v[56:57], s[70:71] offset:256
	v_cvt_pk_bf16_f32 v58, v84, v85
	v_cvt_pk_bf16_f32 v59, v86, v87
	global_store_dwordx2 v54, v[58:59], s[70:71] offset:256
	v_cvt_pk_bf16_f32 v60, v88, v89
	v_cvt_pk_bf16_f32 v61, v90, v91
	global_store_dwordx2 v53, v[60:61], s[70:71] offset:384
	v_cvt_pk_bf16_f32 v62, v92, v93
	v_cvt_pk_bf16_f32 v63, v94, v95
	global_store_dwordx2 v54, v[62:63], s[70:71] offset:384
	s_mov_b32 s80, s89
	s_add_i32 s82, s80, s88
	s_cmp_lt_i32 s82, 0x40000
	s_cselect_b32 s82, s82, s80
	s_lshr_b32 s84, s82, 11
	s_lshl_b32 s84, s84, 4
	s_bfe_u32 s85, s82, 0x40007
	s_or_b32 s84, s84, s85
	s_lshl_b32 s84, s84, 2
	s_add_u32 s72, s48, s84
	s_addc_u32 s73, s49, 0
	s_load_dword s84, s[72:73], 0x0
	s_and_b32 s85, s82, 0x7f
	s_lshl_b32 s85, s85, 11
	s_waitcnt lgkmcnt(0)
	s_mov_b32 s87, 0
	s_mov_b32 s86, s84
	s_lshl_b64 s[86:87], s[86:87], 18
	s_add_u32 s68, s40, s86
	s_addc_u32 s69, s41, s87
	s_add_u32 s68, s68, s85
	s_addc_u32 s69, s69, 0
	global_load_dwordx4 v[64:67], v50, s[68:69] nt
	global_load_dwordx4 v[68:71], v50, s[68:69] offset:1024 nt
	global_load_dwordx4 v[72:75], v50, s[68:69] offset:2048 nt
	global_load_dwordx4 v[76:79], v50, s[68:69] offset:3072 nt
	s_add_u32 s68, s68, 0x1000
	s_addc_u32 s69, s69, 0
	global_load_dwordx4 v[80:83], v50, s[68:69] nt
	global_load_dwordx4 v[84:87], v50, s[68:69] offset:1024 nt
	global_load_dwordx4 v[88:91], v50, s[68:69] offset:2048 nt
	global_load_dwordx4 v[92:95], v50, s[68:69] offset:3072 nt
	s_branch .Lxblk_loop
.Lxblk_exit:
	s_waitcnt vmcnt(0)
.Lxblk_skip:
	s_add_i32 s57, s57, 1
	s_mul_i32 s0, s57, s60
	s_mul_hi_u32 s1, s57, s78
	s_add_i32 s1, s1, s0
	s_mul_i32 s0, s57, s78
	s_add_u32 s20, s0, s66
	s_addc_u32 s21, s1, s33
	v_cmp_gt_i64_e32 vcc, s[20:21], v[144:145]
	v_cmp_lt_i64_e64 s[0:1], s[20:21], v[142:143]
	s_cbranch_vccnz .LBB0_99
	s_ashr_i32 s16, s20, 31
	s_lshr_b32 s16, s16, 29
	s_add_i32 s16, s20, s16
	s_ashr_i32 s17, s16, 3
	s_and_b32 s16, s16, -8
	s_sub_i32 s16, s20, s16
	s_cmp_lt_i32 s16, 0
	s_cselect_b32 s18, s52, 0x176
	s_mul_i32 s16, s16, s18
	s_add_i32 s16, s16, s17
	s_mul_hi_i32 s17, s16, 0x2e8ba2e9
	s_lshr_b32 s18, s17, 31
	s_ashr_i32 s17, s17, 6
	s_add_i32 s17, s17, s18
	s_lshl_b32 s18, s17, 3
	s_sub_i32 s19, 0x44, s18
	s_min_i32 s19, s19, 8
	s_abs_i32 s20, s19
	v_cvt_f32_u32_e32 v2, s20
	s_sub_i32 s22, 0, s20
	s_mulk_i32 s17, 0x160
	s_sub_i32 s17, s16, s17
	v_rcp_iflag_f32_e32 v2, v2
	s_abs_i32 s16, s17
	s_xor_b32 s21, s17, s19
	s_ashr_i32 s21, s21, 31
	v_mul_f32_e32 v2, 0x4f7ffffe, v2
	v_cvt_u32_f32_e32 v2, v2
	s_nop 0
	v_readfirstlane_b32 s23, v2
	s_mul_i32 s22, s22, s23
	s_mul_hi_u32 s22, s23, s22
	s_add_i32 s23, s23, s22
	s_mul_hi_u32 s22, s16, s23
	s_mul_i32 s23, s22, s20
	s_sub_i32 s16, s16, s23
	s_add_i32 s50, s22, 1
	s_sub_i32 s23, s16, s20
	s_cmp_ge_u32 s16, s20
	s_cselect_b32 s22, s50, s22
	s_cselect_b32 s16, s23, s16
	s_add_i32 s23, s22, 1
	s_cmp_ge_u32 s16, s20
	s_cselect_b32 s16, s23, s22
	s_xor_b32 s16, s16, s21
	s_sub_i32 s16, s16, s21
	s_mul_i32 s19, s16, s19
	s_sub_i32 s17, s17, s19
	s_add_i32 s18, s18, s17

; __global__ void __launch_bounds__(NWAVES * 64, 2) hybrid_fwd(Args args) {
;     ...
;         if (!(F.vcu & 1)) { __syncthreads(); xblk_part(F, F.vcu, F.G); }
.LBB0_107:
	s_andn2_b64 vcc, exec, s[8:9]
	s_cbranch_vccnz .LBB0_111
	s_lshl_b32 s0, s96, 5
	s_lshl_b32 s1, s28, 2
	s_add_i32 s8, s1, s0
	s_cmp_gt_i32 s8, 0x3ffff
	s_waitcnt vmcnt(0) lgkmcnt(0)
	s_barrier
	s_branch .LBB0_111
	s_lshl_b32 s0, s96, 12
	s_lshl_b32 s1, s28, 9
	v_lshlrev_b32_e32 v2, 2, v1
	s_add_i32 s10, s0, s1
	s_lshl_b32 s0, s96, 11
	s_lshl_b32 s1, s28, 8
	v_or_b32_e32 v6, 0x100, v2
	v_and_b32_e32 v8, 60, v2
	s_add_i32 s12, s0, s1
	s_lshl_b32 s0, s96, 14
	s_lshl_b32 s1, s28, 11
	v_mov_b32_e32 v3, 0
	v_bfe_u32 v4, v146, 4, 2
	s_lshl_b32 s9, s78, 5
	s_lshl_b32 s11, s78, 12
	s_lshl_b32 s13, s78, 11
	s_add_i32 s14, s0, s1
	s_lshl_b32 s15, s78, 14
	s_mov_b32 s1, 0
	v_lshlrev_b32_e32 v5, 2, v2
	v_lshlrev_b32_e32 v6, 2, v6
	v_lshlrev_b32_e32 v2, 1, v8
	s_mov_b64 s[6:7], 0x8800000
